# n1 + gate/up conv+SiLU epilogue arithmetic rewritten by hand (fmac_dpp row_shr/shl, packed f32 SiLU; 1321->729 lines)
# speedup vs baseline: 1.0118x; 1.0118x over previous
.LBB0_999:
	s_or_b64 exec, exec, s[22:23]
	s_lshl_b32 s22, s20, 7
	v_add_u32_e32 v128, s22, v171
	v_ashrrev_i32_e32 v129, 31, v128
	v_lshl_add_u64 v[128:129], v[128:129], 2, s[54:55]
	global_load_dword v129, v[128:129], off
	v_mov_b32_e32 v150, 0
	s_and_b64 vcc, exec, s[10:11]
	v_mov_b32_e32 v128, 0
	v_mov_b32_e32 v130, 0
	v_mov_b32_e32 v131, 0
	s_waitcnt vmcnt(0)
	ds_write_b32 v173, v129
	s_waitcnt lgkmcnt(0)
	s_barrier
	v_mov_b32_e32 v192, 0xbfb8aa3b
	v_mov_b32_e32 v193, 0xbfb8aa3b
	v_mov_b32_e32 v194, 1.0
	v_mov_b32_e32 v195, 1.0
	v_lshl_add_u32 v181, s24, 8, v165
	v_or_b32_e32 v182, s22, v167
	v_ashrrev_i32_e32 v183, 31, v182
	v_lshlrev_b64 v[182:183], 1, v[182:183]
	s_movk_i32 s2, 0x2c00
	ds_read_b128 v[128:131], v174 offset:0
	ds_read_b128 v[132:135], v174 offset:512
	ds_read_b128 v[136:139], v174 offset:1024
	ds_read_b128 v[140:143], v174 offset:1536
	v_mov_b64_e32 v[200:201], 0
	v_mov_b64_e32 v[202:203], 0
	v_mov_b64_e32 v[204:205], 0
	v_mov_b64_e32 v[206:207], 0
	s_and_b64 vcc, exec, s[10:11]
	s_cbranch_vccz .Lepi_a0
	ds_read_b128 v[200:203], v178
.Lepi_a0:
	s_and_b64 vcc, exec, s[12:13]
	s_cbranch_vccz .Lepi_b0
	ds_read_b128 v[204:207], v172 offset:1024
.Lepi_b0:
	s_waitcnt lgkmcnt(0)
	v_cndmask_b32_e64 v184, 0, v128, s[14:15]
	v_cndmask_b32_e64 v185, 0, v129, s[14:15]
	v_cndmask_b32_e64 v186, 0, v130, s[14:15]
	v_cndmask_b32_e64 v187, 0, v131, s[14:15]
	v_cndmask_b32_e64 v188, 0, v136, s[16:17]
	v_cndmask_b32_e64 v189, 0, v137, s[16:17]
	v_cndmask_b32_e64 v190, 0, v138, s[16:17]
	v_cndmask_b32_e64 v191, 0, v139, s[16:17]
	v_pk_fma_f32 v[208:209], v[24:25], v[132:133], v[140:141]
	v_pk_fma_f32 v[210:211], v[26:27], v[134:135], v[142:143]
	v_pk_fma_f32 v[212:213], v[124:125], v[132:133], v[140:141]
	v_pk_fma_f32 v[214:215], v[126:127], v[134:135], v[142:143]
	v_pk_fma_f32 v[216:217], v[116:117], v[132:133], v[140:141]
	v_pk_fma_f32 v[218:219], v[118:119], v[134:135], v[142:143]
	v_pk_fma_f32 v[220:221], v[104:105], v[132:133], v[140:141]
	v_pk_fma_f32 v[222:223], v[106:107], v[134:135], v[142:143]
	v_fmac_f32_dpp v208, v24, v128 row_shr:1 row_mask:0xf bank_mask:0xf
	v_fmac_f32_dpp v209, v25, v129 row_shr:1 row_mask:0xf bank_mask:0xf
	v_fmac_f32_dpp v210, v26, v130 row_shr:1 row_mask:0xf bank_mask:0xf
	v_fmac_f32_dpp v211, v27, v131 row_shr:1 row_mask:0xf bank_mask:0xf
	v_fmac_f32_dpp v212, v124, v128 row_shr:1 row_mask:0xf bank_mask:0xf
	v_fmac_f32_dpp v213, v125, v129 row_shr:1 row_mask:0xf bank_mask:0xf
	v_fmac_f32_dpp v214, v126, v130 row_shr:1 row_mask:0xf bank_mask:0xf
	v_fmac_f32_dpp v215, v127, v131 row_shr:1 row_mask:0xf bank_mask:0xf
	v_fmac_f32_dpp v216, v116, v128 row_shr:1 row_mask:0xf bank_mask:0xf
	v_fmac_f32_dpp v217, v117, v129 row_shr:1 row_mask:0xf bank_mask:0xf
	v_fmac_f32_dpp v218, v118, v130 row_shr:1 row_mask:0xf bank_mask:0xf
	v_fmac_f32_dpp v219, v119, v131 row_shr:1 row_mask:0xf bank_mask:0xf
	v_fmac_f32_dpp v220, v104, v128 row_shr:1 row_mask:0xf bank_mask:0xf
	v_fmac_f32_dpp v221, v105, v129 row_shr:1 row_mask:0xf bank_mask:0xf
	v_fmac_f32_dpp v222, v106, v130 row_shr:1 row_mask:0xf bank_mask:0xf
	v_fmac_f32_dpp v223, v107, v131 row_shr:1 row_mask:0xf bank_mask:0xf
	v_fmac_f32_dpp v208, v24, v136 row_shl:1 row_mask:0xf bank_mask:0xf
	v_fmac_f32_dpp v209, v25, v137 row_shl:1 row_mask:0xf bank_mask:0xf
	v_fmac_f32_dpp v210, v26, v138 row_shl:1 row_mask:0xf bank_mask:0xf
	v_fmac_f32_dpp v211, v27, v139 row_shl:1 row_mask:0xf bank_mask:0xf
	v_fmac_f32_dpp v212, v124, v136 row_shl:1 row_mask:0xf bank_mask:0xf
	v_fmac_f32_dpp v213, v125, v137 row_shl:1 row_mask:0xf bank_mask:0xf
	v_fmac_f32_dpp v214, v126, v138 row_shl:1 row_mask:0xf bank_mask:0xf
	v_fmac_f32_dpp v215, v127, v139 row_shl:1 row_mask:0xf bank_mask:0xf
	v_fmac_f32_dpp v216, v116, v136 row_shl:1 row_mask:0xf bank_mask:0xf
	v_fmac_f32_dpp v217, v117, v137 row_shl:1 row_mask:0xf bank_mask:0xf
	v_fmac_f32_dpp v218, v118, v138 row_shl:1 row_mask:0xf bank_mask:0xf
	v_fmac_f32_dpp v219, v119, v139 row_shl:1 row_mask:0xf bank_mask:0xf
	v_fmac_f32_dpp v220, v104, v136 row_shl:1 row_mask:0xf bank_mask:0xf
	v_fmac_f32_dpp v221, v105, v137 row_shl:1 row_mask:0xf bank_mask:0xf
	v_fmac_f32_dpp v222, v106, v138 row_shl:1 row_mask:0xf bank_mask:0xf
	v_fmac_f32_dpp v223, v107, v139 row_shl:1 row_mask:0xf bank_mask:0xf
	v_fmac_f32_e32 v208, v200, v184
	v_fmac_f32_e32 v209, v201, v185
	v_fmac_f32_e32 v210, v202, v186
	v_fmac_f32_e32 v211, v203, v187
	v_fmac_f32_dpp v212, v24, v184 row_ror:1 row_mask:0xf bank_mask:0xf
	v_fmac_f32_dpp v213, v25, v185 row_ror:1 row_mask:0xf bank_mask:0xf
	v_fmac_f32_dpp v214, v26, v186 row_ror:1 row_mask:0xf bank_mask:0xf
	v_fmac_f32_dpp v215, v27, v187 row_ror:1 row_mask:0xf bank_mask:0xf
	v_fmac_f32_dpp v216, v124, v184 row_ror:1 row_mask:0xf bank_mask:0xf
	v_fmac_f32_dpp v217, v125, v185 row_ror:1 row_mask:0xf bank_mask:0xf
	v_fmac_f32_dpp v218, v126, v186 row_ror:1 row_mask:0xf bank_mask:0xf
	v_fmac_f32_dpp v219, v127, v187 row_ror:1 row_mask:0xf bank_mask:0xf
	v_fmac_f32_dpp v220, v116, v184 row_ror:1 row_mask:0xf bank_mask:0xf
	v_fmac_f32_dpp v221, v117, v185 row_ror:1 row_mask:0xf bank_mask:0xf
	v_fmac_f32_dpp v222, v118, v186 row_ror:1 row_mask:0xf bank_mask:0xf
	v_fmac_f32_dpp v223, v119, v187 row_ror:1 row_mask:0xf bank_mask:0xf
	v_fmac_f32_dpp v208, v124, v188 row_ror:15 row_mask:0xf bank_mask:0xf
	v_fmac_f32_dpp v209, v125, v189 row_ror:15 row_mask:0xf bank_mask:0xf
	v_fmac_f32_dpp v210, v126, v190 row_ror:15 row_mask:0xf bank_mask:0xf
	v_fmac_f32_dpp v211, v127, v191 row_ror:15 row_mask:0xf bank_mask:0xf
	v_fmac_f32_dpp v212, v116, v188 row_ror:15 row_mask:0xf bank_mask:0xf
	v_fmac_f32_dpp v213, v117, v189 row_ror:15 row_mask:0xf bank_mask:0xf
	v_fmac_f32_dpp v214, v118, v190 row_ror:15 row_mask:0xf bank_mask:0xf
	v_fmac_f32_dpp v215, v119, v191 row_ror:15 row_mask:0xf bank_mask:0xf
	v_fmac_f32_dpp v216, v104, v188 row_ror:15 row_mask:0xf bank_mask:0xf
	v_fmac_f32_dpp v217, v105, v189 row_ror:15 row_mask:0xf bank_mask:0xf
	v_fmac_f32_dpp v218, v106, v190 row_ror:15 row_mask:0xf bank_mask:0xf
	v_fmac_f32_dpp v219, v107, v191 row_ror:15 row_mask:0xf bank_mask:0xf
	v_fmac_f32_e32 v220, v204, v188
	v_fmac_f32_e32 v221, v205, v189
	v_fmac_f32_e32 v222, v206, v190
	v_fmac_f32_e32 v223, v207, v191
	ds_read_b128 v[128:131], v174 offset:16
	ds_read_b128 v[132:135], v174 offset:528
	ds_read_b128 v[136:139], v174 offset:1040
	ds_read_b128 v[140:143], v174 offset:1552
	v_mov_b64_e32 v[200:201], 0
	v_mov_b64_e32 v[202:203], 0
	v_mov_b64_e32 v[204:205], 0
	v_mov_b64_e32 v[206:207], 0
	s_and_b64 vcc, exec, s[10:11]
	s_cbranch_vccz .Lepi_a1
	ds_read_b128 v[200:203], v179
.Lepi_a1:
	s_and_b64 vcc, exec, s[12:13]
	s_cbranch_vccz .Lepi_b1
	ds_read_b128 v[204:207], v172 offset:1040
.Lepi_b1:
	v_pk_mul_f32 v[232:233], v[208:209], v[192:193]
	v_pk_mul_f32 v[234:235], v[210:211], v[192:193]
	v_pk_mul_f32 v[236:237], v[212:213], v[192:193]
	v_pk_mul_f32 v[238:239], v[214:215], v[192:193]
	v_exp_f32_e32 v232, v232
	v_exp_f32_e32 v233, v233
	v_exp_f32_e32 v234, v234
	v_exp_f32_e32 v235, v235
	v_exp_f32_e32 v236, v236
	v_exp_f32_e32 v237, v237
	v_exp_f32_e32 v238, v238
	v_exp_f32_e32 v239, v239
	v_pk_add_f32 v[232:233], v[232:233], v[194:195]
	v_pk_add_f32 v[234:235], v[234:235], v[194:195]
	v_pk_add_f32 v[236:237], v[236:237], v[194:195]
	v_pk_add_f32 v[238:239], v[238:239], v[194:195]
	v_rcp_f32_e32 v232, v232
	v_rcp_f32_e32 v233, v233
	v_rcp_f32_e32 v234, v234
	v_rcp_f32_e32 v235, v235
	v_rcp_f32_e32 v236, v236
	v_rcp_f32_e32 v237, v237
	v_rcp_f32_e32 v238, v238
	v_rcp_f32_e32 v239, v239
	v_pk_mul_f32 v[232:233], v[208:209], v[232:233]
	v_pk_mul_f32 v[234:235], v[210:211], v[234:235]
	v_pk_mul_f32 v[236:237], v[212:213], v[236:237]
	v_pk_mul_f32 v[238:239], v[214:215], v[238:239]
	v_pk_mul_f32 v[232:233], v[28:29], v[232:233]
	v_pk_mul_f32 v[234:235], v[30:31], v[234:235]
	v_pk_mul_f32 v[236:237], v[120:121], v[236:237]
	v_pk_mul_f32 v[238:239], v[122:123], v[238:239]
	v_cvt_pk_bf16_f32 v146, v232, v233
	v_cvt_pk_bf16_f32 v147, v234, v235
	v_cvt_pk_bf16_f32 v150, v236, v237
	v_cvt_pk_bf16_f32 v151, v238, v239
	v_pk_mul_f32 v[240:241], v[216:217], v[192:193]
	v_pk_mul_f32 v[242:243], v[218:219], v[192:193]
	v_pk_mul_f32 v[244:245], v[220:221], v[192:193]
	v_pk_mul_f32 v[246:247], v[222:223], v[192:193]
	v_exp_f32_e32 v240, v240
	v_exp_f32_e32 v241, v241
	v_exp_f32_e32 v242, v242
	v_exp_f32_e32 v243, v243
	v_exp_f32_e32 v244, v244
	v_exp_f32_e32 v245, v245
	v_exp_f32_e32 v246, v246
	v_exp_f32_e32 v247, v247
	v_pk_add_f32 v[240:241], v[240:241], v[194:195]
	v_pk_add_f32 v[242:243], v[242:243], v[194:195]
	v_pk_add_f32 v[244:245], v[244:245], v[194:195]
	v_pk_add_f32 v[246:247], v[246:247], v[194:195]
	v_rcp_f32_e32 v240, v240
	v_rcp_f32_e32 v241, v241
	v_rcp_f32_e32 v242, v242
	v_rcp_f32_e32 v243, v243
	v_rcp_f32_e32 v244, v244
	v_rcp_f32_e32 v245, v245
	v_rcp_f32_e32 v246, v246
	v_rcp_f32_e32 v247, v247
	v_pk_mul_f32 v[240:241], v[216:217], v[240:241]
	v_pk_mul_f32 v[242:243], v[218:219], v[242:243]
	v_pk_mul_f32 v[244:245], v[220:221], v[244:245]
	v_pk_mul_f32 v[246:247], v[222:223], v[246:247]
	v_pk_mul_f32 v[240:241], v[112:113], v[240:241]
	v_pk_mul_f32 v[242:243], v[114:115], v[242:243]
	v_pk_mul_f32 v[244:245], v[108:109], v[244:245]
	v_pk_mul_f32 v[246:247], v[110:111], v[246:247]
	v_cvt_pk_bf16_f32 v224, v240, v241
	v_cvt_pk_bf16_f32 v225, v242, v243
	v_cvt_pk_bf16_f32 v248, v244, v245
	v_cvt_pk_bf16_f32 v249, v246, v247
	s_waitcnt lgkmcnt(0)
	v_cndmask_b32_e64 v184, 0, v128, s[14:15]
	v_cndmask_b32_e64 v185, 0, v129, s[14:15]
	v_cndmask_b32_e64 v186, 0, v130, s[14:15]
	v_cndmask_b32_e64 v187, 0, v131, s[14:15]
	v_cndmask_b32_e64 v188, 0, v136, s[16:17]
	v_cndmask_b32_e64 v189, 0, v137, s[16:17]
	v_cndmask_b32_e64 v190, 0, v138, s[16:17]
	v_cndmask_b32_e64 v191, 0, v139, s[16:17]
	v_pk_fma_f32 v[208:209], v[12:13], v[132:133], v[140:141]
	v_pk_fma_f32 v[210:211], v[14:15], v[134:135], v[142:143]
	v_pk_fma_f32 v[212:213], v[100:101], v[132:133], v[140:141]
	v_pk_fma_f32 v[214:215], v[102:103], v[134:135], v[142:143]
	v_pk_fma_f32 v[216:217], v[92:93], v[132:133], v[140:141]
	v_pk_fma_f32 v[218:219], v[94:95], v[134:135], v[142:143]
	v_pk_fma_f32 v[220:221], v[80:81], v[132:133], v[140:141]
	v_pk_fma_f32 v[222:223], v[82:83], v[134:135], v[142:143]
	v_fmac_f32_dpp v208, v12, v128 row_shr:1 row_mask:0xf bank_mask:0xf
	v_fmac_f32_dpp v209, v13, v129 row_shr:1 row_mask:0xf bank_mask:0xf
	v_fmac_f32_dpp v210, v14, v130 row_shr:1 row_mask:0xf bank_mask:0xf
	v_fmac_f32_dpp v211, v15, v131 row_shr:1 row_mask:0xf bank_mask:0xf
	v_fmac_f32_dpp v212, v100, v128 row_shr:1 row_mask:0xf bank_mask:0xf
	v_fmac_f32_dpp v213, v101, v129 row_shr:1 row_mask:0xf bank_mask:0xf
	v_fmac_f32_dpp v214, v102, v130 row_shr:1 row_mask:0xf bank_mask:0xf
	v_fmac_f32_dpp v215, v103, v131 row_shr:1 row_mask:0xf bank_mask:0xf
	v_fmac_f32_dpp v216, v92, v128 row_shr:1 row_mask:0xf bank_mask:0xf
	v_fmac_f32_dpp v217, v93, v129 row_shr:1 row_mask:0xf bank_mask:0xf
	v_fmac_f32_dpp v218, v94, v130 row_shr:1 row_mask:0xf bank_mask:0xf
	v_fmac_f32_dpp v219, v95, v131 row_shr:1 row_mask:0xf bank_mask:0xf
	v_fmac_f32_dpp v220, v80, v128 row_shr:1 row_mask:0xf bank_mask:0xf
	v_fmac_f32_dpp v221, v81, v129 row_shr:1 row_mask:0xf bank_mask:0xf
	v_fmac_f32_dpp v222, v82, v130 row_shr:1 row_mask:0xf bank_mask:0xf
	v_fmac_f32_dpp v223, v83, v131 row_shr:1 row_mask:0xf bank_mask:0xf
	v_fmac_f32_dpp v208, v12, v136 row_shl:1 row_mask:0xf bank_mask:0xf
	v_fmac_f32_dpp v209, v13, v137 row_shl:1 row_mask:0xf bank_mask:0xf
	v_fmac_f32_dpp v210, v14, v138 row_shl:1 row_mask:0xf bank_mask:0xf
	v_fmac_f32_dpp v211, v15, v139 row_shl:1 row_mask:0xf bank_mask:0xf
	v_fmac_f32_dpp v212, v100, v136 row_shl:1 row_mask:0xf bank_mask:0xf
	v_fmac_f32_dpp v213, v101, v137 row_shl:1 row_mask:0xf bank_mask:0xf
	v_fmac_f32_dpp v214, v102, v138 row_shl:1 row_mask:0xf bank_mask:0xf
	v_fmac_f32_dpp v215, v103, v139 row_shl:1 row_mask:0xf bank_mask:0xf
	v_fmac_f32_dpp v216, v92, v136 row_shl:1 row_mask:0xf bank_mask:0xf
	v_fmac_f32_dpp v217, v93, v137 row_shl:1 row_mask:0xf bank_mask:0xf
	v_fmac_f32_dpp v218, v94, v138 row_shl:1 row_mask:0xf bank_mask:0xf
	v_fmac_f32_dpp v219, v95, v139 row_shl:1 row_mask:0xf bank_mask:0xf
	v_fmac_f32_dpp v220, v80, v136 row_shl:1 row_mask:0xf bank_mask:0xf
	v_fmac_f32_dpp v221, v81, v137 row_shl:1 row_mask:0xf bank_mask:0xf
	v_fmac_f32_dpp v222, v82, v138 row_shl:1 row_mask:0xf bank_mask:0xf
	v_fmac_f32_dpp v223, v83, v139 row_shl:1 row_mask:0xf bank_mask:0xf
	v_fmac_f32_e32 v208, v200, v184
	v_fmac_f32_e32 v209, v201, v185
	v_fmac_f32_e32 v210, v202, v186
	v_fmac_f32_e32 v211, v203, v187
	v_fmac_f32_dpp v212, v12, v184 row_ror:1 row_mask:0xf bank_mask:0xf
	v_fmac_f32_dpp v213, v13, v185 row_ror:1 row_mask:0xf bank_mask:0xf
	v_fmac_f32_dpp v214, v14, v186 row_ror:1 row_mask:0xf bank_mask:0xf
	v_fmac_f32_dpp v215, v15, v187 row_ror:1 row_mask:0xf bank_mask:0xf
	v_fmac_f32_dpp v216, v100, v184 row_ror:1 row_mask:0xf bank_mask:0xf
	v_fmac_f32_dpp v217, v101, v185 row_ror:1 row_mask:0xf bank_mask:0xf
	v_fmac_f32_dpp v218, v102, v186 row_ror:1 row_mask:0xf bank_mask:0xf
	v_fmac_f32_dpp v219, v103, v187 row_ror:1 row_mask:0xf bank_mask:0xf
	v_fmac_f32_dpp v220, v92, v184 row_ror:1 row_mask:0xf bank_mask:0xf
	v_fmac_f32_dpp v221, v93, v185 row_ror:1 row_mask:0xf bank_mask:0xf
	v_fmac_f32_dpp v222, v94, v186 row_ror:1 row_mask:0xf bank_mask:0xf
	v_fmac_f32_dpp v223, v95, v187 row_ror:1 row_mask:0xf bank_mask:0xf
	v_fmac_f32_dpp v208, v100, v188 row_ror:15 row_mask:0xf bank_mask:0xf
	v_fmac_f32_dpp v209, v101, v189 row_ror:15 row_mask:0xf bank_mask:0xf
	v_fmac_f32_dpp v210, v102, v190 row_ror:15 row_mask:0xf bank_mask:0xf
	v_fmac_f32_dpp v211, v103, v191 row_ror:15 row_mask:0xf bank_mask:0xf
	v_fmac_f32_dpp v212, v92, v188 row_ror:15 row_mask:0xf bank_mask:0xf
	v_fmac_f32_dpp v213, v93, v189 row_ror:15 row_mask:0xf bank_mask:0xf
	v_fmac_f32_dpp v214, v94, v190 row_ror:15 row_mask:0xf bank_mask:0xf
	v_fmac_f32_dpp v215, v95, v191 row_ror:15 row_mask:0xf bank_mask:0xf
	v_fmac_f32_dpp v216, v80, v188 row_ror:15 row_mask:0xf bank_mask:0xf
	v_fmac_f32_dpp v217, v81, v189 row_ror:15 row_mask:0xf bank_mask:0xf
	v_fmac_f32_dpp v218, v82, v190 row_ror:15 row_mask:0xf bank_mask:0xf
	v_fmac_f32_dpp v219, v83, v191 row_ror:15 row_mask:0xf bank_mask:0xf
	v_fmac_f32_e32 v220, v204, v188
	v_fmac_f32_e32 v221, v205, v189
	v_fmac_f32_e32 v222, v206, v190
	v_fmac_f32_e32 v223, v207, v191
	ds_read_b128 v[128:131], v174 offset:0
	ds_read_b128 v[132:135], v174 offset:512
	ds_read_b128 v[136:139], v174 offset:1024
	ds_read_b128 v[140:143], v174 offset:1536
	v_mov_b64_e32 v[200:201], 0
	v_mov_b64_e32 v[202:203], 0
	v_mov_b64_e32 v[204:205], 0
	v_mov_b64_e32 v[206:207], 0
	s_and_b64 vcc, exec, s[52:53]
	s_cbranch_vccz .Lepi_a2
	ds_read_b128 v[200:203], v172 offset:1536
.Lepi_a2:
	s_and_b64 vcc, exec, s[8:9]
	s_cbranch_vccz .Lepi_b2
	ds_read_b128 v[204:207], v172 offset:3072
.Lepi_b2:
	v_pk_mul_f32 v[232:233], v[208:209], v[192:193]
	v_pk_mul_f32 v[234:235], v[210:211], v[192:193]
	v_pk_mul_f32 v[236:237], v[212:213], v[192:193]
	v_pk_mul_f32 v[238:239], v[214:215], v[192:193]
	v_exp_f32_e32 v232, v232
	v_exp_f32_e32 v233, v233
	v_exp_f32_e32 v234, v234
	v_exp_f32_e32 v235, v235
	v_exp_f32_e32 v236, v236
	v_exp_f32_e32 v237, v237
	v_exp_f32_e32 v238, v238
	v_exp_f32_e32 v239, v239
	v_pk_add_f32 v[232:233], v[232:233], v[194:195]
	v_pk_add_f32 v[234:235], v[234:235], v[194:195]
	v_pk_add_f32 v[236:237], v[236:237], v[194:195]
	v_pk_add_f32 v[238:239], v[238:239], v[194:195]
	v_rcp_f32_e32 v232, v232
	v_rcp_f32_e32 v233, v233
	v_rcp_f32_e32 v234, v234
	v_rcp_f32_e32 v235, v235
	v_rcp_f32_e32 v236, v236
	v_rcp_f32_e32 v237, v237
	v_rcp_f32_e32 v238, v238
	v_rcp_f32_e32 v239, v239
	v_pk_mul_f32 v[232:233], v[208:209], v[232:233]
	v_pk_mul_f32 v[234:235], v[210:211], v[234:235]
	v_pk_mul_f32 v[236:237], v[212:213], v[236:237]
	v_pk_mul_f32 v[238:239], v[214:215], v[238:239]
	v_pk_mul_f32 v[232:233], v[20:21], v[232:233]
	v_pk_mul_f32 v[234:235], v[22:23], v[234:235]
	v_pk_mul_f32 v[236:237], v[96:97], v[236:237]
	v_pk_mul_f32 v[238:239], v[98:99], v[238:239]
	v_cvt_pk_bf16_f32 v148, v232, v233
	v_cvt_pk_bf16_f32 v149, v234, v235
	v_cvt_pk_bf16_f32 v152, v236, v237
	v_cvt_pk_bf16_f32 v153, v238, v239
	v_pk_mul_f32 v[240:241], v[216:217], v[192:193]
	v_pk_mul_f32 v[242:243], v[218:219], v[192:193]
	v_pk_mul_f32 v[244:245], v[220:221], v[192:193]
	v_pk_mul_f32 v[246:247], v[222:223], v[192:193]
	v_exp_f32_e32 v240, v240
	v_exp_f32_e32 v241, v241
	v_exp_f32_e32 v242, v242
	v_exp_f32_e32 v243, v243
	v_exp_f32_e32 v244, v244
	v_exp_f32_e32 v245, v245
	v_exp_f32_e32 v246, v246
	v_exp_f32_e32 v247, v247
	v_pk_add_f32 v[240:241], v[240:241], v[194:195]
	v_pk_add_f32 v[242:243], v[242:243], v[194:195]
	v_pk_add_f32 v[244:245], v[244:245], v[194:195]
	v_pk_add_f32 v[246:247], v[246:247], v[194:195]
	v_rcp_f32_e32 v240, v240
	v_rcp_f32_e32 v241, v241
	v_rcp_f32_e32 v242, v242
	v_rcp_f32_e32 v243, v243
	v_rcp_f32_e32 v244, v244
	v_rcp_f32_e32 v245, v245
	v_rcp_f32_e32 v246, v246
	v_rcp_f32_e32 v247, v247
	v_pk_mul_f32 v[240:241], v[216:217], v[240:241]
	v_pk_mul_f32 v[242:243], v[218:219], v[242:243]
	v_pk_mul_f32 v[244:245], v[220:221], v[244:245]
	v_pk_mul_f32 v[246:247], v[222:223], v[246:247]
	v_pk_mul_f32 v[240:241], v[88:89], v[240:241]
	v_pk_mul_f32 v[242:243], v[90:91], v[242:243]
	v_pk_mul_f32 v[244:245], v[84:85], v[244:245]
	v_pk_mul_f32 v[246:247], v[86:87], v[246:247]
	v_cvt_pk_bf16_f32 v226, v240, v241
	v_cvt_pk_bf16_f32 v227, v242, v243
	v_cvt_pk_bf16_f32 v250, v244, v245
	v_cvt_pk_bf16_f32 v251, v246, v247
	v_mov_b64_e32 v[208:209], s[28:29]
	v_add_u32_e32 v196, 0, v181
	v_mad_i64_i32 v[196:197], s[20:21], v196, s2, v[208:209]
	v_lshl_add_u64 v[196:197], v[196:197], 0, v[182:183]
	global_store_dwordx4 v[196:197], v[146:149], off
	s_nop 1
	v_add_u32_e32 v198, 16, v181
	v_mad_i64_i32 v[198:199], s[20:21], v198, s2, v[208:209]
	v_lshl_add_u64 v[198:199], v[198:199], 0, v[182:183]
	global_store_dwordx4 v[198:199], v[150:153], off
	s_nop 1
	v_add_u32_e32 v196, 32, v181
	v_mad_i64_i32 v[196:197], s[20:21], v196, s2, v[208:209]
	v_lshl_add_u64 v[196:197], v[196:197], 0, v[182:183]
	global_store_dwordx4 v[196:197], v[224:227], off
	s_nop 1
	v_add_u32_e32 v198, 48, v181
	v_mad_i64_i32 v[198:199], s[20:21], v198, s2, v[208:209]
	v_lshl_add_u64 v[198:199], v[198:199], 0, v[182:183]
	global_store_dwordx4 v[198:199], v[248:251], off
	s_nop 1
	s_waitcnt lgkmcnt(0)
	v_cndmask_b32_e64 v184, 0, v128, s[14:15]
	v_cndmask_b32_e64 v185, 0, v129, s[14:15]
	v_cndmask_b32_e64 v186, 0, v130, s[14:15]
	v_cndmask_b32_e64 v187, 0, v131, s[14:15]
	v_cndmask_b32_e64 v188, 0, v136, s[16:17]
	v_cndmask_b32_e64 v189, 0, v137, s[16:17]
	v_cndmask_b32_e64 v190, 0, v138, s[16:17]
	v_cndmask_b32_e64 v191, 0, v139, s[16:17]
	v_pk_fma_f32 v[208:209], v[72:73], v[132:133], v[140:141]
	v_pk_fma_f32 v[210:211], v[74:75], v[134:135], v[142:143]
	v_pk_fma_f32 v[212:213], v[68:69], v[132:133], v[140:141]
	v_pk_fma_f32 v[214:215], v[70:71], v[134:135], v[142:143]
	v_pk_fma_f32 v[216:217], v[60:61], v[132:133], v[140:141]
	v_pk_fma_f32 v[218:219], v[62:63], v[134:135], v[142:143]
	v_pk_fma_f32 v[220:221], v[16:17], v[132:133], v[140:141]
	v_pk_fma_f32 v[222:223], v[18:19], v[134:135], v[142:143]
	v_fmac_f32_dpp v208, v72, v128 row_shr:1 row_mask:0xf bank_mask:0xf
	v_fmac_f32_dpp v209, v73, v129 row_shr:1 row_mask:0xf bank_mask:0xf
	v_fmac_f32_dpp v210, v74, v130 row_shr:1 row_mask:0xf bank_mask:0xf
	v_fmac_f32_dpp v211, v75, v131 row_shr:1 row_mask:0xf bank_mask:0xf
	v_fmac_f32_dpp v212, v68, v128 row_shr:1 row_mask:0xf bank_mask:0xf
	v_fmac_f32_dpp v213, v69, v129 row_shr:1 row_mask:0xf bank_mask:0xf
	v_fmac_f32_dpp v214, v70, v130 row_shr:1 row_mask:0xf bank_mask:0xf
	v_fmac_f32_dpp v215, v71, v131 row_shr:1 row_mask:0xf bank_mask:0xf
	v_fmac_f32_dpp v216, v60, v128 row_shr:1 row_mask:0xf bank_mask:0xf
	v_fmac_f32_dpp v217, v61, v129 row_shr:1 row_mask:0xf bank_mask:0xf
	v_fmac_f32_dpp v218, v62, v130 row_shr:1 row_mask:0xf bank_mask:0xf
	v_fmac_f32_dpp v219, v63, v131 row_shr:1 row_mask:0xf bank_mask:0xf
	v_fmac_f32_dpp v220, v16, v128 row_shr:1 row_mask:0xf bank_mask:0xf
	v_fmac_f32_dpp v221, v17, v129 row_shr:1 row_mask:0xf bank_mask:0xf
	v_fmac_f32_dpp v222, v18, v130 row_shr:1 row_mask:0xf bank_mask:0xf
	v_fmac_f32_dpp v223, v19, v131 row_shr:1 row_mask:0xf bank_mask:0xf
	v_fmac_f32_dpp v208, v72, v136 row_shl:1 row_mask:0xf bank_mask:0xf
	v_fmac_f32_dpp v209, v73, v137 row_shl:1 row_mask:0xf bank_mask:0xf
	v_fmac_f32_dpp v210, v74, v138 row_shl:1 row_mask:0xf bank_mask:0xf
	v_fmac_f32_dpp v211, v75, v139 row_shl:1 row_mask:0xf bank_mask:0xf
	v_fmac_f32_dpp v212, v68, v136 row_shl:1 row_mask:0xf bank_mask:0xf
	v_fmac_f32_dpp v213, v69, v137 row_shl:1 row_mask:0xf bank_mask:0xf
	v_fmac_f32_dpp v214, v70, v138 row_shl:1 row_mask:0xf bank_mask:0xf
	v_fmac_f32_dpp v215, v71, v139 row_shl:1 row_mask:0xf bank_mask:0xf
	v_fmac_f32_dpp v216, v60, v136 row_shl:1 row_mask:0xf bank_mask:0xf
	v_fmac_f32_dpp v217, v61, v137 row_shl:1 row_mask:0xf bank_mask:0xf
	v_fmac_f32_dpp v218, v62, v138 row_shl:1 row_mask:0xf bank_mask:0xf
	v_fmac_f32_dpp v219, v63, v139 row_shl:1 row_mask:0xf bank_mask:0xf
	v_fmac_f32_dpp v220, v16, v136 row_shl:1 row_mask:0xf bank_mask:0xf
	v_fmac_f32_dpp v221, v17, v137 row_shl:1 row_mask:0xf bank_mask:0xf
	v_fmac_f32_dpp v222, v18, v138 row_shl:1 row_mask:0xf bank_mask:0xf
	v_fmac_f32_dpp v223, v19, v139 row_shl:1 row_mask:0xf bank_mask:0xf
	v_fmac_f32_e32 v208, v200, v184
	v_fmac_f32_e32 v209, v201, v185
	v_fmac_f32_e32 v210, v202, v186
	v_fmac_f32_e32 v211, v203, v187
	v_fmac_f32_dpp v212, v72, v184 row_ror:1 row_mask:0xf bank_mask:0xf
	v_fmac_f32_dpp v213, v73, v185 row_ror:1 row_mask:0xf bank_mask:0xf
	v_fmac_f32_dpp v214, v74, v186 row_ror:1 row_mask:0xf bank_mask:0xf
	v_fmac_f32_dpp v215, v75, v187 row_ror:1 row_mask:0xf bank_mask:0xf
	v_fmac_f32_dpp v216, v68, v184 row_ror:1 row_mask:0xf bank_mask:0xf
	v_fmac_f32_dpp v217, v69, v185 row_ror:1 row_mask:0xf bank_mask:0xf
	v_fmac_f32_dpp v218, v70, v186 row_ror:1 row_mask:0xf bank_mask:0xf
	v_fmac_f32_dpp v219, v71, v187 row_ror:1 row_mask:0xf bank_mask:0xf
	v_fmac_f32_dpp v220, v60, v184 row_ror:1 row_mask:0xf bank_mask:0xf
	v_fmac_f32_dpp v221, v61, v185 row_ror:1 row_mask:0xf bank_mask:0xf
	v_fmac_f32_dpp v222, v62, v186 row_ror:1 row_mask:0xf bank_mask:0xf
	v_fmac_f32_dpp v223, v63, v187 row_ror:1 row_mask:0xf bank_mask:0xf
	v_fmac_f32_dpp v208, v68, v188 row_ror:15 row_mask:0xf bank_mask:0xf
	v_fmac_f32_dpp v209, v69, v189 row_ror:15 row_mask:0xf bank_mask:0xf
	v_fmac_f32_dpp v210, v70, v190 row_ror:15 row_mask:0xf bank_mask:0xf
	v_fmac_f32_dpp v211, v71, v191 row_ror:15 row_mask:0xf bank_mask:0xf
	v_fmac_f32_dpp v212, v60, v188 row_ror:15 row_mask:0xf bank_mask:0xf
	v_fmac_f32_dpp v213, v61, v189 row_ror:15 row_mask:0xf bank_mask:0xf
	v_fmac_f32_dpp v214, v62, v190 row_ror:15 row_mask:0xf bank_mask:0xf
	v_fmac_f32_dpp v215, v63, v191 row_ror:15 row_mask:0xf bank_mask:0xf
	v_fmac_f32_dpp v216, v16, v188 row_ror:15 row_mask:0xf bank_mask:0xf
	v_fmac_f32_dpp v217, v17, v189 row_ror:15 row_mask:0xf bank_mask:0xf
	v_fmac_f32_dpp v218, v18, v190 row_ror:15 row_mask:0xf bank_mask:0xf
	v_fmac_f32_dpp v219, v19, v191 row_ror:15 row_mask:0xf bank_mask:0xf
	v_fmac_f32_e32 v220, v204, v188
	v_fmac_f32_e32 v221, v205, v189
	v_fmac_f32_e32 v222, v206, v190
	v_fmac_f32_e32 v223, v207, v191
	ds_read_b128 v[128:131], v174 offset:16
	ds_read_b128 v[132:135], v174 offset:528
	ds_read_b128 v[136:139], v174 offset:1040
	ds_read_b128 v[140:143], v174 offset:1552
	v_mov_b64_e32 v[200:201], 0
	v_mov_b64_e32 v[202:203], 0
	v_mov_b64_e32 v[204:205], 0
	v_mov_b64_e32 v[206:207], 0
	s_and_b64 vcc, exec, s[52:53]
	s_cbranch_vccz .Lepi_a3
	ds_read_b128 v[200:203], v172 offset:1552
.Lepi_a3:
	s_and_b64 vcc, exec, s[8:9]
	s_cbranch_vccz .Lepi_b3
	ds_read_b128 v[204:207], v172 offset:3088
.Lepi_b3:
	v_pk_mul_f32 v[232:233], v[208:209], v[192:193]
	v_pk_mul_f32 v[234:235], v[210:211], v[192:193]
	v_pk_mul_f32 v[236:237], v[212:213], v[192:193]
	v_pk_mul_f32 v[238:239], v[214:215], v[192:193]
	v_exp_f32_e32 v232, v232
	v_exp_f32_e32 v233, v233
	v_exp_f32_e32 v234, v234
	v_exp_f32_e32 v235, v235
	v_exp_f32_e32 v236, v236
	v_exp_f32_e32 v237, v237
	v_exp_f32_e32 v238, v238
	v_exp_f32_e32 v239, v239
	v_pk_add_f32 v[232:233], v[232:233], v[194:195]
	v_pk_add_f32 v[234:235], v[234:235], v[194:195]
	v_pk_add_f32 v[236:237], v[236:237], v[194:195]
	v_pk_add_f32 v[238:239], v[238:239], v[194:195]
	v_rcp_f32_e32 v232, v232
	v_rcp_f32_e32 v233, v233
	v_rcp_f32_e32 v234, v234
	v_rcp_f32_e32 v235, v235
	v_rcp_f32_e32 v236, v236
	v_rcp_f32_e32 v237, v237
	v_rcp_f32_e32 v238, v238
	v_rcp_f32_e32 v239, v239
	v_pk_mul_f32 v[232:233], v[208:209], v[232:233]
	v_pk_mul_f32 v[234:235], v[210:211], v[234:235]
	v_pk_mul_f32 v[236:237], v[212:213], v[236:237]
	v_pk_mul_f32 v[238:239], v[214:215], v[238:239]
	v_pk_mul_f32 v[232:233], v[76:77], v[232:233]
	v_pk_mul_f32 v[234:235], v[78:79], v[234:235]
	v_pk_mul_f32 v[236:237], v[64:65], v[236:237]
	v_pk_mul_f32 v[238:239], v[66:67], v[238:239]
	v_cvt_pk_bf16_f32 v146, v232, v233
	v_cvt_pk_bf16_f32 v147, v234, v235
	v_cvt_pk_bf16_f32 v150, v236, v237
	v_cvt_pk_bf16_f32 v151, v238, v239
	v_pk_mul_f32 v[240:241], v[216:217], v[192:193]
	v_pk_mul_f32 v[242:243], v[218:219], v[192:193]
	v_pk_mul_f32 v[244:245], v[220:221], v[192:193]
	v_pk_mul_f32 v[246:247], v[222:223], v[192:193]
	v_exp_f32_e32 v240, v240
	v_exp_f32_e32 v241, v241
	v_exp_f32_e32 v242, v242
	v_exp_f32_e32 v243, v243
	v_exp_f32_e32 v244, v244
	v_exp_f32_e32 v245, v245
	v_exp_f32_e32 v246, v246
	v_exp_f32_e32 v247, v247
	v_pk_add_f32 v[240:241], v[240:241], v[194:195]
	v_pk_add_f32 v[242:243], v[242:243], v[194:195]
	v_pk_add_f32 v[244:245], v[244:245], v[194:195]
	v_pk_add_f32 v[246:247], v[246:247], v[194:195]
	v_rcp_f32_e32 v240, v240
	v_rcp_f32_e32 v241, v241
	v_rcp_f32_e32 v242, v242
	v_rcp_f32_e32 v243, v243
	v_rcp_f32_e32 v244, v244
	v_rcp_f32_e32 v245, v245
	v_rcp_f32_e32 v246, v246
	v_rcp_f32_e32 v247, v247
	v_pk_mul_f32 v[240:241], v[216:217], v[240:241]
	v_pk_mul_f32 v[242:243], v[218:219], v[242:243]
	v_pk_mul_f32 v[244:245], v[220:221], v[244:245]
	v_pk_mul_f32 v[246:247], v[222:223], v[246:247]
	v_pk_mul_f32 v[240:241], v[56:57], v[240:241]
	v_pk_mul_f32 v[242:243], v[58:59], v[242:243]
	v_pk_mul_f32 v[244:245], v[8:9], v[244:245]
	v_pk_mul_f32 v[246:247], v[10:11], v[246:247]
	v_cvt_pk_bf16_f32 v224, v240, v241
	v_cvt_pk_bf16_f32 v225, v242, v243
	v_cvt_pk_bf16_f32 v248, v244, v245
	v_cvt_pk_bf16_f32 v249, v246, v247
	s_waitcnt lgkmcnt(0)
	v_cndmask_b32_e64 v184, 0, v128, s[14:15]
	v_cndmask_b32_e64 v185, 0, v129, s[14:15]
	v_cndmask_b32_e64 v186, 0, v130, s[14:15]
	v_cndmask_b32_e64 v187, 0, v131, s[14:15]
	v_cndmask_b32_e64 v188, 0, v136, s[16:17]
	v_cndmask_b32_e64 v189, 0, v137, s[16:17]
	v_cndmask_b32_e64 v190, 0, v138, s[16:17]
	v_cndmask_b32_e64 v191, 0, v139, s[16:17]
	v_pk_fma_f32 v[208:209], v[48:49], v[132:133], v[140:141]
	v_pk_fma_f32 v[210:211], v[50:51], v[134:135], v[142:143]
	v_pk_fma_f32 v[212:213], v[44:45], v[132:133], v[140:141]
	v_pk_fma_f32 v[214:215], v[46:47], v[134:135], v[142:143]
	v_pk_fma_f32 v[216:217], v[36:37], v[132:133], v[140:141]
	v_pk_fma_f32 v[218:219], v[38:39], v[134:135], v[142:143]
	v_pk_fma_f32 v[220:221], v[0:1], v[132:133], v[140:141]
	v_pk_fma_f32 v[222:223], v[2:3], v[134:135], v[142:143]
	v_fmac_f32_dpp v208, v48, v128 row_shr:1 row_mask:0xf bank_mask:0xf
	v_fmac_f32_dpp v209, v49, v129 row_shr:1 row_mask:0xf bank_mask:0xf
	v_fmac_f32_dpp v210, v50, v130 row_shr:1 row_mask:0xf bank_mask:0xf
	v_fmac_f32_dpp v211, v51, v131 row_shr:1 row_mask:0xf bank_mask:0xf
	v_fmac_f32_dpp v212, v44, v128 row_shr:1 row_mask:0xf bank_mask:0xf
	v_fmac_f32_dpp v213, v45, v129 row_shr:1 row_mask:0xf bank_mask:0xf
	v_fmac_f32_dpp v214, v46, v130 row_shr:1 row_mask:0xf bank_mask:0xf
	v_fmac_f32_dpp v215, v47, v131 row_shr:1 row_mask:0xf bank_mask:0xf
	v_fmac_f32_dpp v216, v36, v128 row_shr:1 row_mask:0xf bank_mask:0xf
	v_fmac_f32_dpp v217, v37, v129 row_shr:1 row_mask:0xf bank_mask:0xf
	v_fmac_f32_dpp v218, v38, v130 row_shr:1 row_mask:0xf bank_mask:0xf
	v_fmac_f32_dpp v219, v39, v131 row_shr:1 row_mask:0xf bank_mask:0xf
	v_fmac_f32_dpp v220, v0, v128 row_shr:1 row_mask:0xf bank_mask:0xf
	v_fmac_f32_dpp v221, v1, v129 row_shr:1 row_mask:0xf bank_mask:0xf
	v_fmac_f32_dpp v222, v2, v130 row_shr:1 row_mask:0xf bank_mask:0xf
	v_fmac_f32_dpp v223, v3, v131 row_shr:1 row_mask:0xf bank_mask:0xf
	v_fmac_f32_dpp v208, v48, v136 row_shl:1 row_mask:0xf bank_mask:0xf
	v_fmac_f32_dpp v209, v49, v137 row_shl:1 row_mask:0xf bank_mask:0xf
	v_fmac_f32_dpp v210, v50, v138 row_shl:1 row_mask:0xf bank_mask:0xf
	v_fmac_f32_dpp v211, v51, v139 row_shl:1 row_mask:0xf bank_mask:0xf
	v_fmac_f32_dpp v212, v44, v136 row_shl:1 row_mask:0xf bank_mask:0xf
	v_fmac_f32_dpp v213, v45, v137 row_shl:1 row_mask:0xf bank_mask:0xf
	v_fmac_f32_dpp v214, v46, v138 row_shl:1 row_mask:0xf bank_mask:0xf
	v_fmac_f32_dpp v215, v47, v139 row_shl:1 row_mask:0xf bank_mask:0xf
	v_fmac_f32_dpp v216, v36, v136 row_shl:1 row_mask:0xf bank_mask:0xf
	v_fmac_f32_dpp v217, v37, v137 row_shl:1 row_mask:0xf bank_mask:0xf
	v_fmac_f32_dpp v218, v38, v138 row_shl:1 row_mask:0xf bank_mask:0xf
	v_fmac_f32_dpp v219, v39, v139 row_shl:1 row_mask:0xf bank_mask:0xf
	v_fmac_f32_dpp v220, v0, v136 row_shl:1 row_mask:0xf bank_mask:0xf
	v_fmac_f32_dpp v221, v1, v137 row_shl:1 row_mask:0xf bank_mask:0xf
	v_fmac_f32_dpp v222, v2, v138 row_shl:1 row_mask:0xf bank_mask:0xf
	v_fmac_f32_dpp v223, v3, v139 row_shl:1 row_mask:0xf bank_mask:0xf
	v_fmac_f32_e32 v208, v200, v184
	v_fmac_f32_e32 v209, v201, v185
	v_fmac_f32_e32 v210, v202, v186
	v_fmac_f32_e32 v211, v203, v187
	v_fmac_f32_dpp v212, v48, v184 row_ror:1 row_mask:0xf bank_mask:0xf
	v_fmac_f32_dpp v213, v49, v185 row_ror:1 row_mask:0xf bank_mask:0xf
	v_fmac_f32_dpp v214, v50, v186 row_ror:1 row_mask:0xf bank_mask:0xf
	v_fmac_f32_dpp v215, v51, v187 row_ror:1 row_mask:0xf bank_mask:0xf
	v_fmac_f32_dpp v216, v44, v184 row_ror:1 row_mask:0xf bank_mask:0xf
	v_fmac_f32_dpp v217, v45, v185 row_ror:1 row_mask:0xf bank_mask:0xf
	v_fmac_f32_dpp v218, v46, v186 row_ror:1 row_mask:0xf bank_mask:0xf
	v_fmac_f32_dpp v219, v47, v187 row_ror:1 row_mask:0xf bank_mask:0xf
	v_fmac_f32_dpp v220, v36, v184 row_ror:1 row_mask:0xf bank_mask:0xf
	v_fmac_f32_dpp v221, v37, v185 row_ror:1 row_mask:0xf bank_mask:0xf
	v_fmac_f32_dpp v222, v38, v186 row_ror:1 row_mask:0xf bank_mask:0xf
	v_fmac_f32_dpp v223, v39, v187 row_ror:1 row_mask:0xf bank_mask:0xf
	v_fmac_f32_dpp v208, v44, v188 row_ror:15 row_mask:0xf bank_mask:0xf
	v_fmac_f32_dpp v209, v45, v189 row_ror:15 row_mask:0xf bank_mask:0xf
	v_fmac_f32_dpp v210, v46, v190 row_ror:15 row_mask:0xf bank_mask:0xf
	v_fmac_f32_dpp v211, v47, v191 row_ror:15 row_mask:0xf bank_mask:0xf
	v_fmac_f32_dpp v212, v36, v188 row_ror:15 row_mask:0xf bank_mask:0xf
	v_fmac_f32_dpp v213, v37, v189 row_ror:15 row_mask:0xf bank_mask:0xf
	v_fmac_f32_dpp v214, v38, v190 row_ror:15 row_mask:0xf bank_mask:0xf
	v_fmac_f32_dpp v215, v39, v191 row_ror:15 row_mask:0xf bank_mask:0xf
	v_fmac_f32_dpp v216, v0, v188 row_ror:15 row_mask:0xf bank_mask:0xf
	v_fmac_f32_dpp v217, v1, v189 row_ror:15 row_mask:0xf bank_mask:0xf
	v_fmac_f32_dpp v218, v2, v190 row_ror:15 row_mask:0xf bank_mask:0xf
	v_fmac_f32_dpp v219, v3, v191 row_ror:15 row_mask:0xf bank_mask:0xf
	v_fmac_f32_e32 v220, v204, v188
	v_fmac_f32_e32 v221, v205, v189
	v_fmac_f32_e32 v222, v206, v190
	v_fmac_f32_e32 v223, v207, v191
	v_pk_mul_f32 v[232:233], v[208:209], v[192:193]
	v_pk_mul_f32 v[234:235], v[210:211], v[192:193]
	v_pk_mul_f32 v[236:237], v[212:213], v[192:193]
	v_pk_mul_f32 v[238:239], v[214:215], v[192:193]
	v_exp_f32_e32 v232, v232
	v_exp_f32_e32 v233, v233
	v_exp_f32_e32 v234, v234
	v_exp_f32_e32 v235, v235
	v_exp_f32_e32 v236, v236
	v_exp_f32_e32 v237, v237
	v_exp_f32_e32 v238, v238
	v_exp_f32_e32 v239, v239
	v_pk_add_f32 v[232:233], v[232:233], v[194:195]
	v_pk_add_f32 v[234:235], v[234:235], v[194:195]
	v_pk_add_f32 v[236:237], v[236:237], v[194:195]
	v_pk_add_f32 v[238:239], v[238:239], v[194:195]
	v_rcp_f32_e32 v232, v232
	v_rcp_f32_e32 v233, v233
	v_rcp_f32_e32 v234, v234
	v_rcp_f32_e32 v235, v235
	v_rcp_f32_e32 v236, v236
	v_rcp_f32_e32 v237, v237
	v_rcp_f32_e32 v238, v238
	v_rcp_f32_e32 v239, v239
	v_pk_mul_f32 v[232:233], v[208:209], v[232:233]
	v_pk_mul_f32 v[234:235], v[210:211], v[234:235]
	v_pk_mul_f32 v[236:237], v[212:213], v[236:237]
	v_pk_mul_f32 v[238:239], v[214:215], v[238:239]
	v_pk_mul_f32 v[232:233], v[52:53], v[232:233]
	v_pk_mul_f32 v[234:235], v[54:55], v[234:235]
	v_pk_mul_f32 v[236:237], v[40:41], v[236:237]
	v_pk_mul_f32 v[238:239], v[42:43], v[238:239]
	v_cvt_pk_bf16_f32 v148, v232, v233
	v_cvt_pk_bf16_f32 v149, v234, v235
	v_cvt_pk_bf16_f32 v152, v236, v237
	v_cvt_pk_bf16_f32 v153, v238, v239
	v_pk_mul_f32 v[240:241], v[216:217], v[192:193]
	v_pk_mul_f32 v[242:243], v[218:219], v[192:193]
	v_pk_mul_f32 v[244:245], v[220:221], v[192:193]
	v_pk_mul_f32 v[246:247], v[222:223], v[192:193]
	v_exp_f32_e32 v240, v240
	v_exp_f32_e32 v241, v241
	v_exp_f32_e32 v242, v242
	v_exp_f32_e32 v243, v243
	v_exp_f32_e32 v244, v244
	v_exp_f32_e32 v245, v245
	v_exp_f32_e32 v246, v246
	v_exp_f32_e32 v247, v247
	v_pk_add_f32 v[240:241], v[240:241], v[194:195]
	v_pk_add_f32 v[242:243], v[242:243], v[194:195]
	v_pk_add_f32 v[244:245], v[244:245], v[194:195]
	v_pk_add_f32 v[246:247], v[246:247], v[194:195]
	v_rcp_f32_e32 v240, v240
	v_rcp_f32_e32 v241, v241
	v_rcp_f32_e32 v242, v242
	v_rcp_f32_e32 v243, v243
	v_rcp_f32_e32 v244, v244
	v_rcp_f32_e32 v245, v245
	v_rcp_f32_e32 v246, v246
	v_rcp_f32_e32 v247, v247
	v_pk_mul_f32 v[240:241], v[216:217], v[240:241]
	v_pk_mul_f32 v[242:243], v[218:219], v[242:243]
	v_pk_mul_f32 v[244:245], v[220:221], v[244:245]
	v_pk_mul_f32 v[246:247], v[222:223], v[246:247]
	v_pk_mul_f32 v[240:241], v[32:33], v[240:241]
	v_pk_mul_f32 v[242:243], v[34:35], v[242:243]
	v_pk_mul_f32 v[244:245], v[4:5], v[244:245]
	v_pk_mul_f32 v[246:247], v[6:7], v[246:247]
	v_cvt_pk_bf16_f32 v226, v240, v241
	v_cvt_pk_bf16_f32 v227, v242, v243
	v_cvt_pk_bf16_f32 v250, v244, v245
	v_cvt_pk_bf16_f32 v251, v246, v247
	v_mov_b64_e32 v[208:209], s[28:29]
	v_add_u32_e32 v196, 128, v181
	v_mad_i64_i32 v[196:197], s[20:21], v196, s2, v[208:209]
	v_lshl_add_u64 v[196:197], v[196:197], 0, v[182:183]
	global_store_dwordx4 v[196:197], v[146:149], off
	s_nop 1
	v_add_u32_e32 v198, 144, v181
	v_mad_i64_i32 v[198:199], s[20:21], v198, s2, v[208:209]
	v_lshl_add_u64 v[198:199], v[198:199], 0, v[182:183]
	global_store_dwordx4 v[198:199], v[150:153], off
	s_nop 1
	v_add_u32_e32 v196, 160, v181
	v_mad_i64_i32 v[196:197], s[20:21], v196, s2, v[208:209]
	v_lshl_add_u64 v[196:197], v[196:197], 0, v[182:183]
	global_store_dwordx4 v[196:197], v[224:227], off
	s_nop 1
	v_add_u32_e32 v198, 176, v181
	v_mad_i64_i32 v[198:199], s[20:21], v198, s2, v[208:209]
	v_lshl_add_u64 v[198:199], v[198:199], 0, v[182:183]
	global_store_dwordx4 v[198:199], v[248:251], off
	s_nop 1
	v_or_b32_e32 v110, s22, v167
	v_ashrrev_i32_e32 v111, 31, v110
	s_and_saveexec_b64 s[20:21], s[4:5]
	s_cbranch_execnz .LBB0_1018
	s_or_b64 exec, exec, s[20:21]
	s_and_saveexec_b64 s[20:21], s[26:27]
	s_cbranch_execnz .LBB0_1021
